# write-through sc1 only on the GEMM epilogues' 16-byte stores (in-proj, branch + partials, out, down); norms, thin, conv tails stay nt
# speedup vs baseline: 1.0158x; 1.0027x over previous
; #define PG8_WAIT_V(n) asm volatile("s_waitcnt vmcnt(" #n ")" ::: "memory")
; #define PG8_BAR __builtin_amdgcn_s_barrier()
; template <class Epi, class Sched, bool I8 = false>
; __device__ __forceinline__ void gemm_phase(LAS unsigned char* lds, const Gemm g, const Sched& S, const Epi& E) {
;     ...
;     PG8_WAIT_V(0);
;     if (!PG8_ALIGN) { if (wr == 0) PG8_BAR; }
;     PG8_BAR;
;     __device__ __forceinline__ void operator()(f32x4 (&acc)[2][2][4][2], const Unit& u, int wr, int wc, int fr, int fq) const {
;         const int row0 = u.pm * BM + wr * 64 + fr, col0 = u.pn * BM + wc * 64 + 8 * fq;
;         float* base = bp + ((size_t)u.seg * MS + (row0 - MP)) * DM + col0;
; #pragma unroll
;         for (int ai = 0; ai < 2; ++ai)
; #pragma unroll
;             for (int m = 0; m < 4; ++m)
; #pragma unroll
;                 for (int bj = 0; bj < 2; ++bj) { float* op = base + (size_t)(ai * HALF + m * 16) * DM + bj * CBJ; *(f32x4*)op = acc[ai][bj][m][0]; *(f32x4*)(op + 4) = acc[ai][bj][m][1]; }
;     }
.LBB0_904:
	v_readlane_b32 s4, v252, 39
	v_readlane_b32 s5, v252, 40
	s_mov_b32 s3, s4
	v_readlane_b32 s4, v252, 41
	v_readlane_b32 s2, v252, 37
	s_mov_b32 s0, s4
	s_lshl_b32 s1, s25, 6
	s_lshl_b32 s3, s3, 8
	s_lshl_b32 s2, s2, 8
	s_or_b32 s1, s2, s1
	s_add_i32 s3, s3, s24
	v_or_b32_e32 v132, s1, v143
	s_ashr_i32 s1, s0, 31
	v_add_u32_e32 v130, s3, v142
	v_add_u32_e32 v134, 0xffffc000, v130
	s_lshl_b64 s[0:1], s[0:1], 23
	v_ashrrev_i32_e32 v135, 31, v134
	s_add_u32 s0, s36, s0
	s_addc_u32 s1, s37, s1
	v_lshlrev_b64 v[134:135], 13, v[134:135]
	v_lshl_add_u64 v[134:135], s[0:1], 0, v[134:135]
	v_ashrrev_i32_e32 v133, 31, v132
	v_lshl_add_u64 v[132:133], v[132:133], 2, v[134:135]
	s_mov_b32 s0, 0x20000
	global_store_dwordx4 v[132:133], v[126:129], off sc1
	global_store_dwordx4 v[132:133], v[122:125], off offset:16 sc1
	global_store_dwordx4 v[132:133], v[106:109], off offset:128 sc1
	global_store_dwordx4 v[132:133], v[98:101], off offset:144 sc1
	s_mov_b32 s24, 0x10000
	v_readlane_b32 s5, v252, 42
	v_add_co_u32_e32 v98, vcc, s0, v132
	s_mov_b32 s0, 0x100000
	s_nop 0
	v_addc_co_u32_e32 v99, vcc, 0, v133, vcc
	global_store_dwordx4 v[98:99], v[118:121], off sc1
	global_store_dwordx4 v[98:99], v[114:117], off offset:16 sc1
	global_store_dwordx4 v[98:99], v[90:93], off offset:128 sc1
	global_store_dwordx4 v[98:99], v[82:85], off offset:144 sc1
	s_nop 1
	v_add_co_u32_e32 v82, vcc, s76, v132
	s_nop 1
	v_addc_co_u32_e32 v83, vcc, 0, v133, vcc
	global_store_dwordx4 v[82:83], v[110:113], off sc1
	global_store_dwordx4 v[82:83], v[102:105], off offset:16 sc1
	global_store_dwordx4 v[82:83], v[78:81], off offset:128 sc1
	global_store_dwordx4 v[82:83], v[74:77], off offset:144 sc1
	s_nop 1
	v_add_co_u32_e32 v74, vcc, s77, v132
	s_nop 1
	v_addc_co_u32_e32 v75, vcc, 0, v133, vcc
	global_store_dwordx4 v[74:75], v[94:97], off sc1
	global_store_dwordx4 v[74:75], v[86:89], off offset:16 sc1
	global_store_dwordx4 v[74:75], v[70:73], off offset:128 sc1
	global_store_dwordx4 v[74:75], v[66:69], off offset:144 sc1
	s_nop 1
	v_add_co_u32_e32 v66, vcc, s0, v132
	s_mov_b32 s0, 0x120000
	s_nop 0
	v_addc_co_u32_e32 v67, vcc, 0, v133, vcc
	global_store_dwordx4 v[66:67], v[62:65], off sc1
	global_store_dwordx4 v[66:67], v[58:61], off offset:16 sc1
	global_store_dwordx4 v[66:67], v[46:49], off offset:128 sc1
	global_store_dwordx4 v[66:67], v[38:41], off offset:144 sc1
	s_nop 1
	v_add_co_u32_e32 v38, vcc, s0, v132
	s_nop 1
	v_addc_co_u32_e32 v39, vcc, 0, v133, vcc
	global_store_dwordx4 v[38:39], v[54:57], off sc1
	global_store_dwordx4 v[38:39], v[50:53], off offset:16 sc1
	global_store_dwordx4 v[38:39], v[30:33], off offset:128 sc1
	global_store_dwordx4 v[38:39], v[22:25], off offset:144 sc1
	s_nop 1
	v_add_co_u32_e32 v22, vcc, 0x140000, v132
	s_nop 1
	v_addc_co_u32_e32 v23, vcc, 0, v133, vcc
	global_store_dwordx4 v[22:23], v[42:45], off sc1
	global_store_dwordx4 v[22:23], v[34:37], off offset:16 sc1
	global_store_dwordx4 v[22:23], v[14:17], off offset:128 sc1
	global_store_dwordx4 v[22:23], v[10:13], off offset:144 sc1
	s_nop 1
	v_add_co_u32_e32 v10, vcc, 0x160000, v132
	s_nop 1
	v_addc_co_u32_e32 v11, vcc, 0, v133, vcc
	global_store_dwordx4 v[10:11], v[26:29], off sc1
	global_store_dwordx4 v[10:11], v[18:21], off offset:16 sc1
	global_store_dwordx4 v[10:11], v[6:9], off offset:128 sc1
	global_store_dwordx4 v[10:11], v[2:5], off offset:144 sc1
	s_waitcnt vmcnt(0)
	s_barrier
